# in-proj epilogue: plain-bf16 output tiles (bq/cq/co and context aq) handled by a hand-written path: in-register quad transpose (DPP) + LDS-transposed row-contiguous dwordx4 stores; other tile classes
# speedup vs baseline: 1.0015x; 1.0015x over previous
.LBB0_347:
	s_mul_hi_u32 s20, s19, 0xaaaaaaab
	s_lshr_b32 s20, s20, 1
	s_mul_i32 s20, s20, 0x24000
	s_waitcnt lgkmcnt(0)
	v_mfma_f32_16x16x32_bf16 v[82:85], v[26:29], v[22:25], v[82:85]
	v_add_u32_e32 v191, s13, v122
	s_mul_hi_u32 s23, s14, 0xaaaaaaab
	s_lshr_b32 s23, s23, 1
	v_mfma_f32_16x16x32_bf16 v[78:81], v[26:29], v[18:21], v[78:81]
	s_mul_i32 s23, s23, 0x24000
	v_subrev_u32_e32 v250, s23, v182
	v_subrev_u32_e32 v251, s23, v201
	v_mfma_f32_16x16x32_bf16 v[74:77], v[26:29], v[10:13], v[74:77]
	v_subrev_u32_e32 v252, s23, v202
	v_mfma_f32_16x16x32_bf16 v[70:73], v[26:29], v[6:9], v[70:73]
	v_subrev_u32_e32 v26, s20, v181
	v_mfma_f32_16x16x32_bf16 v[66:69], v[14:17], v[22:25], v[66:69]
	v_mfma_f32_16x16x32_bf16 v[62:65], v[14:17], v[18:21], v[62:65]
	v_mfma_f32_16x16x32_bf16 v[58:61], v[14:17], v[10:13], v[58:61]
	v_mfma_f32_16x16x32_bf16 v[54:57], v[14:17], v[6:9], v[54:57]
	v_subrev_u32_e32 v14, s20, v203
	v_add_u32_e32 v16, v191, v26
	v_add_u32_e32 v14, v191, v14
	v_mfma_f32_16x16x32_bf16 v[38:41], v[30:33], v[22:25], v[38:41]
	v_subrev_u32_e32 v15, s23, v204
	v_mfma_f32_16x16x32_bf16 v[50:53], v[2:5], v[22:25], v[50:53]
	ds_read_b128 v[22:25], v16
	ds_read_b128 v[222:225], v16 offset:2048
	ds_read_b128 v[226:229], v16 offset:4096
	ds_read_b128 v[230:233], v16 offset:6144
	ds_read_b128 v[234:237], v14 offset:32768
	ds_read_b128 v[238:241], v14 offset:34816
	ds_read_b128 v[242:245], v14 offset:36864
	ds_read_b128 v[246:249], v14 offset:38912
	v_mfma_f32_16x16x32_bf16 v[90:93], v[30:33], v[18:21], v[90:93]
	v_mfma_f32_16x16x32_bf16 v[86:89], v[30:33], v[10:13], v[86:89]
	v_mfma_f32_16x16x32_bf16 v[94:97], v[30:33], v[6:9], v[94:97]
	v_mfma_f32_16x16x32_bf16 v[46:49], v[2:5], v[18:21], v[46:49]
	v_mfma_f32_16x16x32_bf16 v[42:45], v[2:5], v[10:13], v[42:45]
	v_mfma_f32_16x16x32_bf16 v[34:37], v[2:5], v[6:9], v[34:37]
	s_add_i32 s20, s6, 4
	s_mul_i32 s23, s20, 0xab
	s_bfe_u32 s23, s23, 0x70009
	s_mul_i32 s23, s23, 3
	s_sub_i32 s20, s20, s23
	s_and_b32 s20, s20, 0xff
	s_mul_i32 s20, s20, 0xc000
	s_waitcnt vmcnt(6)
	v_add_u32_e32 v2, v191, v15
	v_add_u32_e32 v6, v191, v252
	s_waitcnt lgkmcnt(0)
	v_mfma_f32_16x16x32_bf16 v[82:85], v[222:225], v[234:237], v[82:85]
	s_add_i32 s23, s20, s11
	s_waitcnt lgkmcnt(0)
	s_barrier
	v_mfma_f32_16x16x32_bf16 v[78:81], v[222:225], v[238:241], v[78:81]
	ds_read_b128 v[30:33], v2
	ds_read_b128 v[26:29], v2 offset:2048
	ds_read_b128 v[14:17], v2 offset:4096
	ds_read_b128 v[2:5], v2 offset:6144
	v_add_u32_e32 v7, v191, v251
	v_mfma_f32_16x16x32_bf16 v[74:77], v[222:225], v[242:245], v[74:77]
	s_mov_b32 m0, s23
	s_mov_b64 s[34:35], 0x180
	s_add_i32 s20, s20, s12
	v_mfma_f32_16x16x32_bf16 v[70:73], v[222:225], v[246:249], v[70:73]
	v_lshl_add_u64 v[222:223], v[118:119], 0, v[102:103]
	v_lshl_add_u64 v[224:225], v[222:223], 0, s[84:85]
	s_add_i32 s19, s19, 1
	v_mfma_f32_16x16x32_bf16 v[38:41], v[22:25], v[234:237], v[38:41]
	v_mfma_f32_16x16x32_bf16 v[90:93], v[22:25], v[238:241], v[90:93]
	v_mfma_f32_16x16x32_bf16 v[86:89], v[22:25], v[242:245], v[86:89]
	v_mfma_f32_16x16x32_bf16 v[94:97], v[22:25], v[246:249], v[94:97]
	ds_read_b128 v[22:25], v6
	ds_read_b128 v[18:21], v7
	v_add_u32_e32 v6, v191, v250
	ds_read_b128 v[10:13], v6
	ds_read_b128 v[6:9], v6 offset:2048
	global_load_lds_dwordx4 v[224:225], off
	v_lshl_add_u64 v[224:225], v[222:223], 0, s[76:77]
	s_add_i32 m0, s23, 0x400
	v_mfma_f32_16x16x32_bf16 v[66:69], v[226:229], v[234:237], v[66:69]
	global_load_lds_dwordx4 v[224:225], off
	v_lshl_add_u64 v[224:225], v[222:223], 0, s[54:55]
	s_add_i32 m0, s23, 0x800
	v_lshl_add_u64 v[222:223], v[222:223], 0, s[68:69]
	global_load_lds_dwordx4 v[224:225], off
	s_add_i32 m0, s23, 0xc00
	v_mfma_f32_16x16x32_bf16 v[62:65], v[226:229], v[238:241], v[62:65]
	global_load_lds_dwordx4 v[222:223], off
	v_lshl_add_u64 v[222:223], v[120:121], 0, v[102:103]
	v_lshl_add_u64 v[224:225], v[222:223], 0, s[34:35]
	s_add_i32 m0, s20, 0x8000
	s_mov_b64 s[34:35], 0x4180
	global_load_lds_dwordx4 v[224:225], off
	v_lshl_add_u64 v[222:223], v[222:223], 0, s[34:35]
	s_add_i32 m0, s20, 0x8400
	v_mfma_f32_16x16x32_bf16 v[58:61], v[226:229], v[242:245], v[58:61]
	global_load_lds_dwordx4 v[222:223], off
	v_mfma_f32_16x16x32_bf16 v[54:57], v[226:229], v[246:249], v[54:57]
	v_mfma_f32_16x16x32_bf16 v[50:53], v[230:233], v[234:237], v[50:53]
	v_mfma_f32_16x16x32_bf16 v[46:49], v[230:233], v[238:241], v[46:49]
	v_mfma_f32_16x16x32_bf16 v[42:45], v[230:233], v[242:245], v[42:45]
	v_mfma_f32_16x16x32_bf16 v[34:37], v[230:233], v[246:249], v[34:37]
	s_add_i32 s6, s6, 1
	s_add_i32 s13, s13, 0xc000
	s_add_i32 s14, s14, 1
	v_lshl_add_u64 v[118:119], v[118:119], 0, s[2:3]
	s_cmp_eq_u32 s13, 0x9c000
	v_lshl_add_u64 v[120:121], v[120:121], 0, s[2:3]
	s_cbranch_scc0 .LBB0_347
	s_waitcnt lgkmcnt(0)
	v_mfma_f32_16x16x32_bf16 v[38:41], v[30:33], v[22:25], v[38:41]
	v_mfma_f32_16x16x32_bf16 v[90:93], v[30:33], v[18:21], v[90:93]
	v_mfma_f32_16x16x32_bf16 v[86:89], v[30:33], v[10:13], v[86:89]
	v_mfma_f32_16x16x32_bf16 v[30:33], v[30:33], v[6:9], v[94:97]
	v_mfma_f32_16x16x32_bf16 v[82:85], v[26:29], v[22:25], v[82:85]
	v_mfma_f32_16x16x32_bf16 v[78:81], v[26:29], v[18:21], v[78:81]
	v_mfma_f32_16x16x32_bf16 v[74:77], v[26:29], v[10:13], v[74:77]
	v_mfma_f32_16x16x32_bf16 v[26:29], v[26:29], v[6:9], v[70:73]
	v_mfma_f32_16x16x32_bf16 v[66:69], v[14:17], v[22:25], v[66:69]
	v_mfma_f32_16x16x32_bf16 v[62:65], v[14:17], v[18:21], v[62:65]
	v_mfma_f32_16x16x32_bf16 v[58:61], v[14:17], v[10:13], v[58:61]
	v_mfma_f32_16x16x32_bf16 v[14:17], v[14:17], v[6:9], v[54:57]
	v_mfma_f32_16x16x32_bf16 v[22:25], v[2:5], v[22:25], v[50:53]
	v_mfma_f32_16x16x32_bf16 v[18:21], v[2:5], v[18:21], v[46:49]
	s_nop 2
	ds_read_b128 v[46:49], v205
	ds_read_b128 v[50:53], v206 offset:2048
	ds_read_b128 v[54:57], v206 offset:4096
	ds_read_b128 v[70:73], v206 offset:6144
	v_mfma_f32_16x16x32_bf16 v[10:13], v[2:5], v[10:13], v[42:45]
	s_nop 2
	ds_read_b128 v[42:45], v207 offset:32768
	ds_read_b128 v[94:97], v208 offset:34816
	ds_read_b128 v[118:121], v208 offset:36864
	ds_read_b128 v[222:225], v208 offset:38912
	v_mfma_f32_16x16x32_bf16 v[2:5], v[2:5], v[6:9], v[34:37]
	s_waitcnt lgkmcnt(0)
	v_mfma_f32_16x16x32_bf16 v[6:9], v[46:49], v[42:45], v[38:41]
	s_waitcnt vmcnt(6)
	s_waitcnt lgkmcnt(0)
	s_barrier
	v_mfma_f32_16x16x32_bf16 v[34:37], v[46:49], v[94:97], v[90:93]
	v_mfma_f32_16x16x32_bf16 v[38:41], v[46:49], v[118:121], v[86:89]
	s_nop 1
	v_add_u32_e32 v90, 0x20800, v212
	v_mfma_f32_16x16x32_bf16 v[30:33], v[46:49], v[222:225], v[30:33]
	v_mfma_f32_16x16x32_bf16 v[46:49], v[50:53], v[42:45], v[82:85]
	v_mfma_f32_16x16x32_bf16 v[78:81], v[50:53], v[94:97], v[78:81]
	v_mfma_f32_16x16x32_bf16 v[74:77], v[50:53], v[118:121], v[74:77]
	v_mfma_f32_16x16x32_bf16 v[26:29], v[50:53], v[222:225], v[26:29]
	v_mfma_f32_16x16x32_bf16 v[50:53], v[54:57], v[42:45], v[66:69]
	v_mfma_f32_16x16x32_bf16 v[62:65], v[54:57], v[94:97], v[62:65]
	v_mfma_f32_16x16x32_bf16 v[58:61], v[54:57], v[118:121], v[58:61]
	v_mfma_f32_16x16x32_bf16 v[14:17], v[54:57], v[222:225], v[14:17]
	v_add_u32_e32 v54, v180, v124
	ds_read_b128 v[54:57], v54
	ds_read_b128 v[66:69], v209 offset:2048
	v_mfma_f32_16x16x32_bf16 v[18:21], v[70:73], v[94:97], v[18:21]
	v_add_u32_e32 v94, 0x21000, v212
	v_mfma_f32_16x16x32_bf16 v[10:13], v[70:73], v[118:121], v[10:13]
	v_add_u32_e32 v118, 0x21800, v212
	v_mfma_f32_16x16x32_bf16 v[22:25], v[70:73], v[42:45], v[22:25]
	ds_read_b128 v[42:45], v209 offset:4096
	ds_read_b128 v[82:85], v209 offset:6144
	ds_read_b128 v[86:89], v211
	ds_read_b128 v[90:93], v90
	ds_read_b128 v[94:97], v94
	ds_read_b128 v[118:121], v118
	v_mfma_f32_16x16x32_bf16 v[2:5], v[70:73], v[222:225], v[2:5]
	s_waitcnt lgkmcnt(0)
	v_mfma_f32_16x16x32_bf16 v[50:53], v[42:45], v[86:89], v[50:53]
	v_mfma_f32_16x16x32_bf16 v[62:65], v[42:45], v[90:93], v[62:65]
	v_mfma_f32_16x16x32_bf16 v[58:61], v[42:45], v[94:97], v[58:61]
	v_mfma_f32_16x16x32_bf16 v[14:17], v[42:45], v[118:121], v[14:17]
	v_add_u32_e32 v42, v180, v128
	v_mfma_f32_16x16x32_bf16 v[6:9], v[54:57], v[86:89], v[6:9]
	v_mfma_f32_16x16x32_bf16 v[34:37], v[54:57], v[90:93], v[34:37]
	v_mfma_f32_16x16x32_bf16 v[38:41], v[54:57], v[94:97], v[38:41]
	v_mfma_f32_16x16x32_bf16 v[30:33], v[54:57], v[118:121], v[30:33]
	v_mfma_f32_16x16x32_bf16 v[46:49], v[66:69], v[86:89], v[46:49]
	v_mfma_f32_16x16x32_bf16 v[54:57], v[66:69], v[90:93], v[78:81]
	v_mfma_f32_16x16x32_bf16 v[70:73], v[66:69], v[94:97], v[74:77]
	v_mfma_f32_16x16x32_bf16 v[26:29], v[66:69], v[118:121], v[26:29]
	ds_read_b128 v[42:45], v42
	ds_read_b128 v[66:69], v213
	ds_read_b128 v[74:77], v214
	ds_read_b128 v[78:81], v215
	v_mfma_f32_16x16x32_bf16 v[22:25], v[82:85], v[86:89], v[22:25]
	v_mfma_f32_16x16x32_bf16 v[18:21], v[82:85], v[90:93], v[18:21]
	v_mfma_f32_16x16x32_bf16 v[10:13], v[82:85], v[94:97], v[10:13]
	ds_read_b128 v[86:89], v216
	ds_read_b128 v[90:93], v217
	ds_read_b128 v[94:97], v218
	ds_read_b128 v[222:225], v219
	v_mfma_f32_16x16x32_bf16 v[2:5], v[82:85], v[118:121], v[2:5]
	s_waitcnt vmcnt(0)
	s_waitcnt lgkmcnt(0)
	v_mfma_f32_16x16x32_bf16 v[6:9], v[42:45], v[86:89], v[6:9]
	s_waitcnt lgkmcnt(0)
	s_barrier
	v_mfma_f32_16x16x32_bf16 v[34:37], v[42:45], v[90:93], v[34:37]
	v_mfma_f32_16x16x32_bf16 v[38:41], v[42:45], v[94:97], v[38:41]
	v_mfma_f32_16x16x32_bf16 v[30:33], v[42:45], v[222:225], v[30:33]
	v_mfma_f32_16x16x32_bf16 v[42:45], v[66:69], v[86:89], v[46:49]
	v_mfma_f32_16x16x32_bf16 v[46:49], v[66:69], v[90:93], v[54:57]
	v_mfma_f32_16x16x32_bf16 v[54:57], v[66:69], v[94:97], v[70:73]
	v_mfma_f32_16x16x32_bf16 v[26:29], v[66:69], v[222:225], v[26:29]
	v_mfma_f32_16x16x32_bf16 v[50:53], v[74:77], v[86:89], v[50:53]
	v_mfma_f32_16x16x32_bf16 v[62:65], v[74:77], v[90:93], v[62:65]
	v_mfma_f32_16x16x32_bf16 v[58:61], v[74:77], v[94:97], v[58:61]
	v_mfma_f32_16x16x32_bf16 v[14:17], v[74:77], v[222:225], v[14:17]
	ds_read_b128 v[66:69], v212 offset:38912
	ds_read_b128 v[70:73], v212 offset:36864
	ds_read_b128 v[74:77], v212 offset:34816
	ds_read_b128 v[82:85], v210 offset:32768
	v_mfma_f32_16x16x32_bf16 v[22:25], v[78:81], v[86:89], v[22:25]
	v_mfma_f32_16x16x32_bf16 v[18:21], v[78:81], v[90:93], v[18:21]
	v_mfma_f32_16x16x32_bf16 v[10:13], v[78:81], v[94:97], v[10:13]
	ds_read_b128 v[86:89], v221 offset:6144
	ds_read_b128 v[90:93], v221 offset:4096
	ds_read_b128 v[94:97], v221 offset:2048
	ds_read_b128 v[118:121], v117
	v_mfma_f32_16x16x32_bf16 v[2:5], v[78:81], v[222:225], v[2:5]
	s_waitcnt lgkmcnt(0)
	v_mfma_f32_16x16x32_bf16 v[42:45], v[94:97], v[82:85], v[42:45]
	v_add_u32_e32 v78, v123, v128
	v_add_u32_e32 v117, v127, v128
	v_mfma_f32_16x16x32_bf16 v[46:49], v[94:97], v[74:77], v[46:49]
	v_mfma_f32_16x16x32_bf16 v[54:57], v[94:97], v[70:73], v[54:57]
	v_mfma_f32_16x16x32_bf16 v[26:29], v[94:97], v[66:69], v[26:29]
	v_add_u32_e32 v94, v126, v128
	v_mfma_f32_16x16x32_bf16 v[50:53], v[90:93], v[82:85], v[50:53]
	v_mfma_f32_16x16x32_bf16 v[62:65], v[90:93], v[74:77], v[62:65]
	v_mfma_f32_16x16x32_bf16 v[58:61], v[90:93], v[70:73], v[58:61]
	v_mfma_f32_16x16x32_bf16 v[14:17], v[90:93], v[66:69], v[14:17]
	v_add_u32_e32 v90, v125, v128
	v_mfma_f32_16x16x32_bf16 v[6:9], v[118:121], v[82:85], v[6:9]
	v_mfma_f32_16x16x32_bf16 v[34:37], v[118:121], v[74:77], v[34:37]
	v_mfma_f32_16x16x32_bf16 v[38:41], v[118:121], v[70:73], v[38:41]
	v_mfma_f32_16x16x32_bf16 v[30:33], v[118:121], v[66:69], v[30:33]
	v_mfma_f32_16x16x32_bf16 v[22:25], v[86:89], v[82:85], v[22:25]
	ds_read_b128 v[78:81], v78
	ds_read_b128 v[82:85], v90 offset:2048
	v_mfma_f32_16x16x32_bf16 v[18:21], v[86:89], v[74:77], v[18:21]
	ds_read_b128 v[74:77], v90 offset:4096
	ds_read_b128 v[90:93], v90 offset:6144
	v_mfma_f32_16x16x32_bf16 v[10:13], v[86:89], v[70:73], v[10:13]
	ds_read_b128 v[70:73], v94 offset:32768
	ds_read_b128 v[94:97], v117 offset:34816
	ds_read_b128 v[118:121], v117 offset:36864
	ds_read_b128 v[222:225], v117 offset:38912
	v_mfma_f32_16x16x32_bf16 v[2:5], v[86:89], v[66:69], v[2:5]
	s_waitcnt vmcnt(0)
	s_waitcnt lgkmcnt(0)
	s_waitcnt lgkmcnt(0)
	v_mfma_f32_16x16x32_bf16 v[6:9], v[78:81], v[70:73], v[6:9]
	s_barrier
	v_mfma_f32_16x16x32_bf16 v[34:37], v[78:81], v[94:97], v[34:37]
	v_mfma_f32_16x16x32_bf16 v[38:41], v[78:81], v[118:121], v[38:41]
	v_mfma_f32_16x16x32_bf16 v[30:33], v[78:81], v[222:225], v[30:33]
	v_mfma_f32_16x16x32_bf16 v[42:45], v[82:85], v[70:73], v[42:45]
	v_mfma_f32_16x16x32_bf16 v[46:49], v[82:85], v[94:97], v[46:49]
	v_mfma_f32_16x16x32_bf16 v[54:57], v[82:85], v[118:121], v[54:57]
	v_mfma_f32_16x16x32_bf16 v[26:29], v[82:85], v[222:225], v[26:29]
	v_mfma_f32_16x16x32_bf16 v[50:53], v[74:77], v[70:73], v[50:53]
	v_mfma_f32_16x16x32_bf16 v[62:65], v[74:77], v[94:97], v[62:65]
	v_mfma_f32_16x16x32_bf16 v[58:61], v[74:77], v[118:121], v[58:61]
	v_mfma_f32_16x16x32_bf16 v[14:17], v[74:77], v[222:225], v[14:17]
	v_mfma_f32_16x16x32_bf16 v[22:25], v[90:93], v[70:73], v[22:25]
	v_mfma_f32_16x16x32_bf16 v[18:21], v[90:93], v[94:97], v[18:21]
	v_mfma_f32_16x16x32_bf16 v[10:13], v[90:93], v[118:121], v[10:13]
	v_mfma_f32_16x16x32_bf16 v[2:5], v[90:93], v[222:225], v[2:5]
	s_waitcnt lgkmcnt(0)
	s_barrier
	v_mov_b32_e32 v230, s75
	v_mov_b32_e32 v231, 0xaaaaaaab
	v_mul_hi_u32 v231, v230, v231
	v_lshrrev_b32_e32 v231, 4, v231
	v_mul_u32_u24_e32 v232, 24, v231
	v_sub_u32_e32 v232, v230, v232
	v_lshrrev_b32_e32 v233, 6, v137
	v_and_b32_e32 v234, 1, v233
	v_lshlrev_b32_e32 v231, 7, v231
	v_lshl_add_u32 v231, v234, 6, v231
	v_lshrrev_b32_e32 v231, 8, v231
	v_lshrrev_b32_e32 v233, 1, v233
	v_lshlrev_b32_e32 v232, 8, v232
	v_lshl_add_u32 v232, v233, 6, v232
	v_mov_b32_e32 v235, 0x1240
	v_lshrrev_b32_e32 v235, v231, v235
	v_and_b32_e32 v235, 1, v235
	v_cmp_gt_u32_e32 vcc, 2, v231
	s_nop 1
	v_cndmask_b32_e64 v236, 0, 1, vcc
	v_cmp_gt_u32_e32 vcc, 0x1000, v232
	s_nop 1
	v_cndmask_b32_e64 v237, 0, 1, vcc
	v_and_b32_e32 v236, v236, v237
	v_or_b32_e32 v235, v235, v236
	v_cmp_ne_u32_e32 vcc, 0, v235
	s_nop 4
	s_cmp_lg_u64 vcc, 0
	s_cbranch_scc0 .Lipe_fallback
	s_mul_hi_i32 s6, s75, 0x2aaaaaab
	s_lshr_b32 s13, s6, 31
	s_ashr_i32 s6, s6, 2
	s_add_i32 s6, s6, s13
	s_mul_i32 s13, s6, 24
	s_sub_i32 s13, s75, s13
	v_readfirstlane_b32 s14, v137
	s_lshr_b32 s14, s14, 6
	s_and_b32 s19, s14, 1
	s_lshr_b32 s20, s14, 1
	s_lshl_b32 s13, s13, 8
	s_lshl_b32 s20, s20, 6
	s_add_i32 s13, s13, s20
	s_lshl_b32 s6, s6, 7
	s_lshl_b32 s19, s19, 6
	s_add_i32 s6, s6, s19
	s_mul_i32 s14, s14, 0x4100
	v_and_b32_e32 v221, 63, v137
	v_and_b32_e32 v222, 15, v221
	v_lshrrev_b32_e32 v223, 4, v221
	v_and_b32_e32 v224, 3, v222
	v_lshrrev_b32_e32 v225, 2, v222
	v_lshl_or_b32 v226, v223, 2, v224
	s_mov_b32 s34, 0xaaaaaaaa
	s_mov_b32 s35, 0xaaaaaaaa
	s_mov_b32 s36, 0xcccccccc
	s_mov_b32 s37, 0xcccccccc
	s_nop 1
	v_mov_b32_dpp v66, v7 quad_perm:[1,0,3,2] row_mask:0xf bank_mask:0xf
	v_mov_b32_dpp v67, v6 quad_perm:[1,0,3,2] row_mask:0xf bank_mask:0xf
	v_mov_b32_dpp v68, v9 quad_perm:[1,0,3,2] row_mask:0xf bank_mask:0xf
	v_mov_b32_dpp v69, v8 quad_perm:[1,0,3,2] row_mask:0xf bank_mask:0xf
	v_cndmask_b32_e64 v6, v6, v66, s[34:35]
	v_cndmask_b32_e64 v7, v67, v7, s[34:35]
	v_cndmask_b32_e64 v8, v8, v68, s[34:35]
	v_cndmask_b32_e64 v9, v69, v9, s[34:35]
	s_nop 1
	v_mov_b32_dpp v68, v6 quad_perm:[2,3,0,1] row_mask:0xf bank_mask:0xf
	v_mov_b32_dpp v69, v7 quad_perm:[2,3,0,1] row_mask:0xf bank_mask:0xf
	v_mov_b32_dpp v66, v8 quad_perm:[2,3,0,1] row_mask:0xf bank_mask:0xf
	v_mov_b32_dpp v67, v9 quad_perm:[2,3,0,1] row_mask:0xf bank_mask:0xf
	v_cndmask_b32_e64 v6, v6, v66, s[36:37]
	v_cndmask_b32_e64 v7, v7, v67, s[36:37]
	v_cndmask_b32_e64 v8, v68, v8, s[36:37]
	v_cndmask_b32_e64 v9, v69, v9, s[36:37]
	s_nop 1
	v_mov_b32_dpp v66, v35 quad_perm:[1,0,3,2] row_mask:0xf bank_mask:0xf
	v_mov_b32_dpp v67, v34 quad_perm:[1,0,3,2] row_mask:0xf bank_mask:0xf
	v_mov_b32_dpp v68, v37 quad_perm:[1,0,3,2] row_mask:0xf bank_mask:0xf
	v_mov_b32_dpp v69, v36 quad_perm:[1,0,3,2] row_mask:0xf bank_mask:0xf
	v_cndmask_b32_e64 v34, v34, v66, s[34:35]
	v_cndmask_b32_e64 v35, v67, v35, s[34:35]
	v_cndmask_b32_e64 v36, v36, v68, s[34:35]
	v_cndmask_b32_e64 v37, v69, v37, s[34:35]
	s_nop 1
	v_mov_b32_dpp v68, v34 quad_perm:[2,3,0,1] row_mask:0xf bank_mask:0xf
	v_mov_b32_dpp v69, v35 quad_perm:[2,3,0,1] row_mask:0xf bank_mask:0xf
	v_mov_b32_dpp v66, v36 quad_perm:[2,3,0,1] row_mask:0xf bank_mask:0xf
	v_mov_b32_dpp v67, v37 quad_perm:[2,3,0,1] row_mask:0xf bank_mask:0xf
	v_cndmask_b32_e64 v34, v34, v66, s[36:37]
	v_cndmask_b32_e64 v35, v35, v67, s[36:37]
	v_cndmask_b32_e64 v36, v68, v36, s[36:37]
	v_cndmask_b32_e64 v37, v69, v37, s[36:37]
	s_nop 1
	v_mov_b32_dpp v66, v39 quad_perm:[1,0,3,2] row_mask:0xf bank_mask:0xf
	v_mov_b32_dpp v67, v38 quad_perm:[1,0,3,2] row_mask:0xf bank_mask:0xf
	v_mov_b32_dpp v68, v41 quad_perm:[1,0,3,2] row_mask:0xf bank_mask:0xf
	v_mov_b32_dpp v69, v40 quad_perm:[1,0,3,2] row_mask:0xf bank_mask:0xf
	v_cndmask_b32_e64 v38, v38, v66, s[34:35]
	v_cndmask_b32_e64 v39, v67, v39, s[34:35]
	v_cndmask_b32_e64 v40, v40, v68, s[34:35]
	v_cndmask_b32_e64 v41, v69, v41, s[34:35]
	s_nop 1
	v_mov_b32_dpp v68, v38 quad_perm:[2,3,0,1] row_mask:0xf bank_mask:0xf
	v_mov_b32_dpp v69, v39 quad_perm:[2,3,0,1] row_mask:0xf bank_mask:0xf
	v_mov_b32_dpp v66, v40 quad_perm:[2,3,0,1] row_mask:0xf bank_mask:0xf
	v_mov_b32_dpp v67, v41 quad_perm:[2,3,0,1] row_mask:0xf bank_mask:0xf
	v_cndmask_b32_e64 v38, v38, v66, s[36:37]
	v_cndmask_b32_e64 v39, v39, v67, s[36:37]
	v_cndmask_b32_e64 v40, v68, v40, s[36:37]
	v_cndmask_b32_e64 v41, v69, v41, s[36:37]
	s_nop 1
	v_mov_b32_dpp v66, v31 quad_perm:[1,0,3,2] row_mask:0xf bank_mask:0xf
	v_mov_b32_dpp v67, v30 quad_perm:[1,0,3,2] row_mask:0xf bank_mask:0xf
	v_mov_b32_dpp v68, v33 quad_perm:[1,0,3,2] row_mask:0xf bank_mask:0xf
	v_mov_b32_dpp v69, v32 quad_perm:[1,0,3,2] row_mask:0xf bank_mask:0xf
	v_cndmask_b32_e64 v30, v30, v66, s[34:35]
	v_cndmask_b32_e64 v31, v67, v31, s[34:35]
	v_cndmask_b32_e64 v32, v32, v68, s[34:35]
	v_cndmask_b32_e64 v33, v69, v33, s[34:35]
	s_nop 1
	v_mov_b32_dpp v68, v30 quad_perm:[2,3,0,1] row_mask:0xf bank_mask:0xf
	v_mov_b32_dpp v69, v31 quad_perm:[2,3,0,1] row_mask:0xf bank_mask:0xf
	v_mov_b32_dpp v66, v32 quad_perm:[2,3,0,1] row_mask:0xf bank_mask:0xf
	v_mov_b32_dpp v67, v33 quad_perm:[2,3,0,1] row_mask:0xf bank_mask:0xf
	v_cndmask_b32_e64 v30, v30, v66, s[36:37]
	v_cndmask_b32_e64 v31, v31, v67, s[36:37]
	v_cndmask_b32_e64 v32, v68, v32, s[36:37]
	v_cndmask_b32_e64 v33, v69, v33, s[36:37]
	s_nop 1
	v_mov_b32_dpp v66, v43 quad_perm:[1,0,3,2] row_mask:0xf bank_mask:0xf
	v_mov_b32_dpp v67, v42 quad_perm:[1,0,3,2] row_mask:0xf bank_mask:0xf
	v_mov_b32_dpp v68, v45 quad_perm:[1,0,3,2] row_mask:0xf bank_mask:0xf
	v_mov_b32_dpp v69, v44 quad_perm:[1,0,3,2] row_mask:0xf bank_mask:0xf
	v_cndmask_b32_e64 v42, v42, v66, s[34:35]
	v_cndmask_b32_e64 v43, v67, v43, s[34:35]
	v_cndmask_b32_e64 v44, v44, v68, s[34:35]
	v_cndmask_b32_e64 v45, v69, v45, s[34:35]
	s_nop 1
	v_mov_b32_dpp v68, v42 quad_perm:[2,3,0,1] row_mask:0xf bank_mask:0xf
	v_mov_b32_dpp v69, v43 quad_perm:[2,3,0,1] row_mask:0xf bank_mask:0xf
	v_mov_b32_dpp v66, v44 quad_perm:[2,3,0,1] row_mask:0xf bank_mask:0xf
	v_mov_b32_dpp v67, v45 quad_perm:[2,3,0,1] row_mask:0xf bank_mask:0xf
	v_cndmask_b32_e64 v42, v42, v66, s[36:37]
	v_cndmask_b32_e64 v43, v43, v67, s[36:37]
	v_cndmask_b32_e64 v44, v68, v44, s[36:37]
	v_cndmask_b32_e64 v45, v69, v45, s[36:37]
	s_nop 1
	v_mov_b32_dpp v66, v47 quad_perm:[1,0,3,2] row_mask:0xf bank_mask:0xf
	v_mov_b32_dpp v67, v46 quad_perm:[1,0,3,2] row_mask:0xf bank_mask:0xf
	v_mov_b32_dpp v68, v49 quad_perm:[1,0,3,2] row_mask:0xf bank_mask:0xf
	v_mov_b32_dpp v69, v48 quad_perm:[1,0,3,2] row_mask:0xf bank_mask:0xf
	v_cndmask_b32_e64 v46, v46, v66, s[34:35]
	v_cndmask_b32_e64 v47, v67, v47, s[34:35]
	v_cndmask_b32_e64 v48, v48, v68, s[34:35]
	v_cndmask_b32_e64 v49, v69, v49, s[34:35]
	s_nop 1
	v_mov_b32_dpp v68, v46 quad_perm:[2,3,0,1] row_mask:0xf bank_mask:0xf
	v_mov_b32_dpp v69, v47 quad_perm:[2,3,0,1] row_mask:0xf bank_mask:0xf
	v_mov_b32_dpp v66, v48 quad_perm:[2,3,0,1] row_mask:0xf bank_mask:0xf
	v_mov_b32_dpp v67, v49 quad_perm:[2,3,0,1] row_mask:0xf bank_mask:0xf
	v_cndmask_b32_e64 v46, v46, v66, s[36:37]
	v_cndmask_b32_e64 v47, v47, v67, s[36:37]
	v_cndmask_b32_e64 v48, v68, v48, s[36:37]
	v_cndmask_b32_e64 v49, v69, v49, s[36:37]
	s_nop 1
	v_mov_b32_dpp v66, v55 quad_perm:[1,0,3,2] row_mask:0xf bank_mask:0xf
	v_mov_b32_dpp v67, v54 quad_perm:[1,0,3,2] row_mask:0xf bank_mask:0xf
	v_mov_b32_dpp v68, v57 quad_perm:[1,0,3,2] row_mask:0xf bank_mask:0xf
	v_mov_b32_dpp v69, v56 quad_perm:[1,0,3,2] row_mask:0xf bank_mask:0xf
	v_cndmask_b32_e64 v54, v54, v66, s[34:35]
	v_cndmask_b32_e64 v55, v67, v55, s[34:35]
	v_cndmask_b32_e64 v56, v56, v68, s[34:35]
	v_cndmask_b32_e64 v57, v69, v57, s[34:35]
	s_nop 1
	v_mov_b32_dpp v68, v54 quad_perm:[2,3,0,1] row_mask:0xf bank_mask:0xf
	v_mov_b32_dpp v69, v55 quad_perm:[2,3,0,1] row_mask:0xf bank_mask:0xf
	v_mov_b32_dpp v66, v56 quad_perm:[2,3,0,1] row_mask:0xf bank_mask:0xf
	v_mov_b32_dpp v67, v57 quad_perm:[2,3,0,1] row_mask:0xf bank_mask:0xf
	v_cndmask_b32_e64 v54, v54, v66, s[36:37]
	v_cndmask_b32_e64 v55, v55, v67, s[36:37]
	v_cndmask_b32_e64 v56, v68, v56, s[36:37]
	v_cndmask_b32_e64 v57, v69, v57, s[36:37]
	s_nop 1
	v_mov_b32_dpp v66, v27 quad_perm:[1,0,3,2] row_mask:0xf bank_mask:0xf
	v_mov_b32_dpp v67, v26 quad_perm:[1,0,3,2] row_mask:0xf bank_mask:0xf
	v_mov_b32_dpp v68, v29 quad_perm:[1,0,3,2] row_mask:0xf bank_mask:0xf
	v_mov_b32_dpp v69, v28 quad_perm:[1,0,3,2] row_mask:0xf bank_mask:0xf
	v_cndmask_b32_e64 v26, v26, v66, s[34:35]
	v_cndmask_b32_e64 v27, v67, v27, s[34:35]
	v_cndmask_b32_e64 v28, v28, v68, s[34:35]
	v_cndmask_b32_e64 v29, v69, v29, s[34:35]
	s_nop 1
	v_mov_b32_dpp v68, v26 quad_perm:[2,3,0,1] row_mask:0xf bank_mask:0xf
	v_mov_b32_dpp v69, v27 quad_perm:[2,3,0,1] row_mask:0xf bank_mask:0xf
	v_mov_b32_dpp v66, v28 quad_perm:[2,3,0,1] row_mask:0xf bank_mask:0xf
	v_mov_b32_dpp v67, v29 quad_perm:[2,3,0,1] row_mask:0xf bank_mask:0xf
	v_cndmask_b32_e64 v26, v26, v66, s[36:37]
	v_cndmask_b32_e64 v27, v27, v67, s[36:37]
	v_cndmask_b32_e64 v28, v68, v28, s[36:37]
	v_cndmask_b32_e64 v29, v69, v29, s[36:37]
	s_nop 1
	v_mov_b32_dpp v66, v51 quad_perm:[1,0,3,2] row_mask:0xf bank_mask:0xf
	v_mov_b32_dpp v67, v50 quad_perm:[1,0,3,2] row_mask:0xf bank_mask:0xf
	v_mov_b32_dpp v68, v53 quad_perm:[1,0,3,2] row_mask:0xf bank_mask:0xf
	v_mov_b32_dpp v69, v52 quad_perm:[1,0,3,2] row_mask:0xf bank_mask:0xf
	v_cndmask_b32_e64 v50, v50, v66, s[34:35]
	v_cndmask_b32_e64 v51, v67, v51, s[34:35]
	v_cndmask_b32_e64 v52, v52, v68, s[34:35]
	v_cndmask_b32_e64 v53, v69, v53, s[34:35]
	s_nop 1
	v_mov_b32_dpp v68, v50 quad_perm:[2,3,0,1] row_mask:0xf bank_mask:0xf
	v_mov_b32_dpp v69, v51 quad_perm:[2,3,0,1] row_mask:0xf bank_mask:0xf
	v_mov_b32_dpp v66, v52 quad_perm:[2,3,0,1] row_mask:0xf bank_mask:0xf
	v_mov_b32_dpp v67, v53 quad_perm:[2,3,0,1] row_mask:0xf bank_mask:0xf
	v_cndmask_b32_e64 v50, v50, v66, s[36:37]
	v_cndmask_b32_e64 v51, v51, v67, s[36:37]
	v_cndmask_b32_e64 v52, v68, v52, s[36:37]
	v_cndmask_b32_e64 v53, v69, v53, s[36:37]
	s_nop 1
	v_mov_b32_dpp v66, v63 quad_perm:[1,0,3,2] row_mask:0xf bank_mask:0xf
	v_mov_b32_dpp v67, v62 quad_perm:[1,0,3,2] row_mask:0xf bank_mask:0xf
	v_mov_b32_dpp v68, v65 quad_perm:[1,0,3,2] row_mask:0xf bank_mask:0xf
	v_mov_b32_dpp v69, v64 quad_perm:[1,0,3,2] row_mask:0xf bank_mask:0xf
	v_cndmask_b32_e64 v62, v62, v66, s[34:35]
	v_cndmask_b32_e64 v63, v67, v63, s[34:35]
	v_cndmask_b32_e64 v64, v64, v68, s[34:35]
	v_cndmask_b32_e64 v65, v69, v65, s[34:35]
	s_nop 1
	v_mov_b32_dpp v68, v62 quad_perm:[2,3,0,1] row_mask:0xf bank_mask:0xf
	v_mov_b32_dpp v69, v63 quad_perm:[2,3,0,1] row_mask:0xf bank_mask:0xf
	v_mov_b32_dpp v66, v64 quad_perm:[2,3,0,1] row_mask:0xf bank_mask:0xf
	v_mov_b32_dpp v67, v65 quad_perm:[2,3,0,1] row_mask:0xf bank_mask:0xf
	v_cndmask_b32_e64 v62, v62, v66, s[36:37]
	v_cndmask_b32_e64 v63, v63, v67, s[36:37]
	v_cndmask_b32_e64 v64, v68, v64, s[36:37]
	v_cndmask_b32_e64 v65, v69, v65, s[36:37]
	s_nop 1
	v_mov_b32_dpp v66, v59 quad_perm:[1,0,3,2] row_mask:0xf bank_mask:0xf
	v_mov_b32_dpp v67, v58 quad_perm:[1,0,3,2] row_mask:0xf bank_mask:0xf
	v_mov_b32_dpp v68, v61 quad_perm:[1,0,3,2] row_mask:0xf bank_mask:0xf
	v_mov_b32_dpp v69, v60 quad_perm:[1,0,3,2] row_mask:0xf bank_mask:0xf
	v_cndmask_b32_e64 v58, v58, v66, s[34:35]
	v_cndmask_b32_e64 v59, v67, v59, s[34:35]
	v_cndmask_b32_e64 v60, v60, v68, s[34:35]
	v_cndmask_b32_e64 v61, v69, v61, s[34:35]
	s_nop 1
	v_mov_b32_dpp v68, v58 quad_perm:[2,3,0,1] row_mask:0xf bank_mask:0xf
	v_mov_b32_dpp v69, v59 quad_perm:[2,3,0,1] row_mask:0xf bank_mask:0xf
	v_mov_b32_dpp v66, v60 quad_perm:[2,3,0,1] row_mask:0xf bank_mask:0xf
	v_mov_b32_dpp v67, v61 quad_perm:[2,3,0,1] row_mask:0xf bank_mask:0xf
	v_cndmask_b32_e64 v58, v58, v66, s[36:37]
	v_cndmask_b32_e64 v59, v59, v67, s[36:37]
	v_cndmask_b32_e64 v60, v68, v60, s[36:37]
	v_cndmask_b32_e64 v61, v69, v61, s[36:37]
	s_nop 1
	v_mov_b32_dpp v66, v15 quad_perm:[1,0,3,2] row_mask:0xf bank_mask:0xf
	v_mov_b32_dpp v67, v14 quad_perm:[1,0,3,2] row_mask:0xf bank_mask:0xf
	v_mov_b32_dpp v68, v17 quad_perm:[1,0,3,2] row_mask:0xf bank_mask:0xf
	v_mov_b32_dpp v69, v16 quad_perm:[1,0,3,2] row_mask:0xf bank_mask:0xf
	v_cndmask_b32_e64 v14, v14, v66, s[34:35]
	v_cndmask_b32_e64 v15, v67, v15, s[34:35]
	v_cndmask_b32_e64 v16, v16, v68, s[34:35]
	v_cndmask_b32_e64 v17, v69, v17, s[34:35]
	s_nop 1
	v_mov_b32_dpp v68, v14 quad_perm:[2,3,0,1] row_mask:0xf bank_mask:0xf
	v_mov_b32_dpp v69, v15 quad_perm:[2,3,0,1] row_mask:0xf bank_mask:0xf
	v_mov_b32_dpp v66, v16 quad_perm:[2,3,0,1] row_mask:0xf bank_mask:0xf
	v_mov_b32_dpp v67, v17 quad_perm:[2,3,0,1] row_mask:0xf bank_mask:0xf
	v_cndmask_b32_e64 v14, v14, v66, s[36:37]
	v_cndmask_b32_e64 v15, v15, v67, s[36:37]
	v_cndmask_b32_e64 v16, v68, v16, s[36:37]
	v_cndmask_b32_e64 v17, v69, v17, s[36:37]
	s_nop 1
	v_mov_b32_dpp v66, v23 quad_perm:[1,0,3,2] row_mask:0xf bank_mask:0xf
	v_mov_b32_dpp v67, v22 quad_perm:[1,0,3,2] row_mask:0xf bank_mask:0xf
	v_mov_b32_dpp v68, v25 quad_perm:[1,0,3,2] row_mask:0xf bank_mask:0xf
	v_mov_b32_dpp v69, v24 quad_perm:[1,0,3,2] row_mask:0xf bank_mask:0xf
	v_cndmask_b32_e64 v22, v22, v66, s[34:35]
	v_cndmask_b32_e64 v23, v67, v23, s[34:35]
	v_cndmask_b32_e64 v24, v24, v68, s[34:35]
	v_cndmask_b32_e64 v25, v69, v25, s[34:35]
	s_nop 1
	v_mov_b32_dpp v68, v22 quad_perm:[2,3,0,1] row_mask:0xf bank_mask:0xf
	v_mov_b32_dpp v69, v23 quad_perm:[2,3,0,1] row_mask:0xf bank_mask:0xf
	v_mov_b32_dpp v66, v24 quad_perm:[2,3,0,1] row_mask:0xf bank_mask:0xf
	v_mov_b32_dpp v67, v25 quad_perm:[2,3,0,1] row_mask:0xf bank_mask:0xf
	v_cndmask_b32_e64 v22, v22, v66, s[36:37]
	v_cndmask_b32_e64 v23, v23, v67, s[36:37]
	v_cndmask_b32_e64 v24, v68, v24, s[36:37]
	v_cndmask_b32_e64 v25, v69, v25, s[36:37]
	s_nop 1
	v_mov_b32_dpp v66, v19 quad_perm:[1,0,3,2] row_mask:0xf bank_mask:0xf
	v_mov_b32_dpp v67, v18 quad_perm:[1,0,3,2] row_mask:0xf bank_mask:0xf
	v_mov_b32_dpp v68, v21 quad_perm:[1,0,3,2] row_mask:0xf bank_mask:0xf
	v_mov_b32_dpp v69, v20 quad_perm:[1,0,3,2] row_mask:0xf bank_mask:0xf
	v_cndmask_b32_e64 v18, v18, v66, s[34:35]
	v_cndmask_b32_e64 v19, v67, v19, s[34:35]
	v_cndmask_b32_e64 v20, v20, v68, s[34:35]
	v_cndmask_b32_e64 v21, v69, v21, s[34:35]
	s_nop 1
	v_mov_b32_dpp v68, v18 quad_perm:[2,3,0,1] row_mask:0xf bank_mask:0xf
	v_mov_b32_dpp v69, v19 quad_perm:[2,3,0,1] row_mask:0xf bank_mask:0xf
	v_mov_b32_dpp v66, v20 quad_perm:[2,3,0,1] row_mask:0xf bank_mask:0xf
	v_mov_b32_dpp v67, v21 quad_perm:[2,3,0,1] row_mask:0xf bank_mask:0xf
	v_cndmask_b32_e64 v18, v18, v66, s[36:37]
	v_cndmask_b32_e64 v19, v19, v67, s[36:37]
	v_cndmask_b32_e64 v20, v68, v20, s[36:37]
	v_cndmask_b32_e64 v21, v69, v21, s[36:37]
	s_nop 1
	v_mov_b32_dpp v66, v11 quad_perm:[1,0,3,2] row_mask:0xf bank_mask:0xf
	v_mov_b32_dpp v67, v10 quad_perm:[1,0,3,2] row_mask:0xf bank_mask:0xf
	v_mov_b32_dpp v68, v13 quad_perm:[1,0,3,2] row_mask:0xf bank_mask:0xf
	v_mov_b32_dpp v69, v12 quad_perm:[1,0,3,2] row_mask:0xf bank_mask:0xf
	v_cndmask_b32_e64 v10, v10, v66, s[34:35]
	v_cndmask_b32_e64 v11, v67, v11, s[34:35]
	v_cndmask_b32_e64 v12, v12, v68, s[34:35]
	v_cndmask_b32_e64 v13, v69, v13, s[34:35]
	s_nop 1
	v_mov_b32_dpp v68, v10 quad_perm:[2,3,0,1] row_mask:0xf bank_mask:0xf
	v_mov_b32_dpp v69, v11 quad_perm:[2,3,0,1] row_mask:0xf bank_mask:0xf
	v_mov_b32_dpp v66, v12 quad_perm:[2,3,0,1] row_mask:0xf bank_mask:0xf
	v_mov_b32_dpp v67, v13 quad_perm:[2,3,0,1] row_mask:0xf bank_mask:0xf
	v_cndmask_b32_e64 v10, v10, v66, s[36:37]
	v_cndmask_b32_e64 v11, v11, v67, s[36:37]
	v_cndmask_b32_e64 v12, v68, v12, s[36:37]
	v_cndmask_b32_e64 v13, v69, v13, s[36:37]
	s_nop 1
	v_mov_b32_dpp v66, v3 quad_perm:[1,0,3,2] row_mask:0xf bank_mask:0xf
	v_mov_b32_dpp v67, v2 quad_perm:[1,0,3,2] row_mask:0xf bank_mask:0xf
	v_mov_b32_dpp v68, v5 quad_perm:[1,0,3,2] row_mask:0xf bank_mask:0xf
	v_mov_b32_dpp v69, v4 quad_perm:[1,0,3,2] row_mask:0xf bank_mask:0xf
	v_cndmask_b32_e64 v2, v2, v66, s[34:35]
	v_cndmask_b32_e64 v3, v67, v3, s[34:35]
	v_cndmask_b32_e64 v4, v4, v68, s[34:35]
	v_cndmask_b32_e64 v5, v69, v5, s[34:35]
	s_nop 1
	v_mov_b32_dpp v68, v2 quad_perm:[2,3,0,1] row_mask:0xf bank_mask:0xf
	v_mov_b32_dpp v69, v3 quad_perm:[2,3,0,1] row_mask:0xf bank_mask:0xf
	v_mov_b32_dpp v66, v4 quad_perm:[2,3,0,1] row_mask:0xf bank_mask:0xf
	v_mov_b32_dpp v67, v5 quad_perm:[2,3,0,1] row_mask:0xf bank_mask:0xf
	v_cndmask_b32_e64 v2, v2, v66, s[36:37]
	v_cndmask_b32_e64 v3, v3, v67, s[36:37]
	v_cndmask_b32_e64 v4, v68, v4, s[36:37]
	v_cndmask_b32_e64 v5, v69, v5, s[36:37]
	v_and_b32_e32 v227, 7, v226
	v_lshlrev_b32_e32 v227, 1, v227
	v_or_b32_e32 v228, 0, v225
	v_xor_b32_e32 v228, v228, v227
	v_lshlrev_b32_e32 v228, 3, v228
	v_lshl_add_u32 v228, v226, 7, v228
	v_add_u32_e32 v228, s14, v228
	v_or_b32_e32 v229, 4, v225
	v_xor_b32_e32 v229, v229, v227
	v_lshlrev_b32_e32 v229, 3, v229
	v_lshl_add_u32 v229, v226, 7, v229
	v_add_u32_e32 v229, s14, v229
	v_or_b32_e32 v230, 8, v225
	v_xor_b32_e32 v230, v230, v227
	v_lshlrev_b32_e32 v230, 3, v230
	v_lshl_add_u32 v230, v226, 7, v230
	v_add_u32_e32 v230, s14, v230
	v_or_b32_e32 v231, 12, v225
	v_xor_b32_e32 v231, v231, v227
	v_lshlrev_b32_e32 v231, 3, v231
	v_lshl_add_u32 v231, v226, 7, v231
	v_add_u32_e32 v231, s14, v231
	v_lshl_add_u32 v232, v221, 4, s14
	v_lshrrev_b32_e32 v233, 3, v221
	v_and_b32_e32 v234, 7, v221
	v_xor_b32_e32 v234, v234, v233
	v_add_u32_e32 v233, s13, v233
	v_mul_u32_u24_e32 v233, 0x1a20, v233
	v_lshl_add_u32 v233, v234, 4, v233
	s_lshl_b32 s16, s6, 1
	v_add_u32_e32 v233, s16, v233
	s_add_u32 s16, s94, 0x8748000
	s_addc_u32 s17, s95, 0
	v_cvt_pk_bf16_f32 v6, v6, v7
	v_cvt_pk_bf16_f32 v7, v8, v9
	ds_write_b64 v228, v[6:7] offset:0
	v_cvt_pk_bf16_f32 v34, v34, v35
	v_cvt_pk_bf16_f32 v35, v36, v37
	ds_write_b64 v229, v[34:35] offset:0
	v_cvt_pk_bf16_f32 v38, v38, v39
	v_cvt_pk_bf16_f32 v39, v40, v41
	ds_write_b64 v230, v[38:39] offset:0
	v_cvt_pk_bf16_f32 v30, v30, v31
	v_cvt_pk_bf16_f32 v31, v32, v33
	ds_write_b64 v231, v[30:31] offset:0
	v_cvt_pk_bf16_f32 v42, v42, v43
	v_cvt_pk_bf16_f32 v43, v44, v45
	ds_write_b64 v228, v[42:43] offset:2048
	v_cvt_pk_bf16_f32 v46, v46, v47
	v_cvt_pk_bf16_f32 v47, v48, v49
	ds_write_b64 v229, v[46:47] offset:2048
	v_cvt_pk_bf16_f32 v54, v54, v55
	v_cvt_pk_bf16_f32 v55, v56, v57
	ds_write_b64 v230, v[54:55] offset:2048
	v_cvt_pk_bf16_f32 v26, v26, v27
	v_cvt_pk_bf16_f32 v27, v28, v29
	ds_write_b64 v231, v[26:27] offset:2048
	v_cvt_pk_bf16_f32 v50, v50, v51
	v_cvt_pk_bf16_f32 v51, v52, v53
	ds_write_b64 v228, v[50:51] offset:4096
	v_cvt_pk_bf16_f32 v62, v62, v63
	v_cvt_pk_bf16_f32 v63, v64, v65
	ds_write_b64 v229, v[62:63] offset:4096
	v_cvt_pk_bf16_f32 v58, v58, v59
	v_cvt_pk_bf16_f32 v59, v60, v61
	ds_write_b64 v230, v[58:59] offset:4096
	v_cvt_pk_bf16_f32 v14, v14, v15
	v_cvt_pk_bf16_f32 v15, v16, v17
	ds_write_b64 v231, v[14:15] offset:4096
	v_cvt_pk_bf16_f32 v22, v22, v23
	v_cvt_pk_bf16_f32 v23, v24, v25
	ds_write_b64 v228, v[22:23] offset:6144
	v_cvt_pk_bf16_f32 v18, v18, v19
	v_cvt_pk_bf16_f32 v19, v20, v21
	ds_write_b64 v229, v[18:19] offset:6144
	v_cvt_pk_bf16_f32 v10, v10, v11
	v_cvt_pk_bf16_f32 v11, v12, v13
	ds_write_b64 v230, v[10:11] offset:6144
	v_cvt_pk_bf16_f32 v2, v2, v3
	v_cvt_pk_bf16_f32 v3, v4, v5
	ds_write_b64 v231, v[2:3] offset:6144
	s_waitcnt lgkmcnt(0)
	ds_read_b128 v[66:69], v232 offset:0
	ds_read_b128 v[70:73], v232 offset:1024
	ds_read_b128 v[74:77], v232 offset:2048
	ds_read_b128 v[78:81], v232 offset:3072
	ds_read_b128 v[82:85], v232 offset:4096
	ds_read_b128 v[86:89], v232 offset:5120
	ds_read_b128 v[90:93], v232 offset:6144
	ds_read_b128 v[94:97], v232 offset:7168
	s_waitcnt lgkmcnt(7)
	global_store_dwordx4 v233, v[66:69], s[16:17]
	s_waitcnt lgkmcnt(6)
	v_add_u32_e32 v235, 0xd100, v233
	global_store_dwordx4 v235, v[70:73], s[16:17]
	s_waitcnt lgkmcnt(5)
	v_add_u32_e32 v235, 0x1a200, v233
	global_store_dwordx4 v235, v[74:77], s[16:17]
	s_waitcnt lgkmcnt(4)
	v_add_u32_e32 v235, 0x27300, v233
	global_store_dwordx4 v235, v[78:81], s[16:17]
	s_waitcnt lgkmcnt(3)
	v_add_u32_e32 v235, 0x34400, v233
	global_store_dwordx4 v235, v[82:85], s[16:17]
	s_waitcnt lgkmcnt(2)
	v_add_u32_e32 v235, 0x41500, v233
	global_store_dwordx4 v235, v[86:89], s[16:17]
	s_waitcnt lgkmcnt(1)
	v_add_u32_e32 v235, 0x4e600, v233
	global_store_dwordx4 v235, v[90:93], s[16:17]
	s_waitcnt lgkmcnt(0)
	v_add_u32_e32 v235, 0x5b700, v233
	global_store_dwordx4 v235, v[94:97], s[16:17]
	s_branch .LBB0_345
.Lipe_fallback:
	ds_write2_b32 v177, v6, v34 offset1:16
	ds_write2_b32 v177, v7, v35 offset0:65 offset1:81
	ds_write2_b32 v177, v8, v36 offset0:130 offset1:146
	ds_write2_b32 v177, v9, v37 offset0:195 offset1:211
	ds_write2_b32 v177, v38, v30 offset0:32 offset1:48
	ds_write2_b32 v177, v39, v31 offset0:97 offset1:113
	ds_write2_b32 v177, v40, v32 offset0:162 offset1:178
	ds_write2_b32 v177, v41, v33 offset0:227 offset1:243
	v_add_u32_e32 v6, 0x1000, v177
	ds_write2_b32 v6, v42, v46 offset0:16 offset1:32
	ds_write2_b32 v6, v43, v47 offset0:81 offset1:97
	ds_write2_b32 v6, v44, v48 offset0:146 offset1:162
	ds_write2_b32 v6, v45, v49 offset0:211 offset1:227
	ds_write2_b32 v6, v54, v26 offset0:48 offset1:64
	ds_write2_b32 v6, v55, v27 offset0:113 offset1:129
	ds_write2_b32 v6, v56, v28 offset0:178 offset1:194
	v_add_u32_e32 v6, 0x1200, v177
	ds_write2_b32 v6, v57, v29 offset0:115 offset1:131
	v_add_u32_e32 v6, 0x2000, v177
	ds_write2_b32 v6, v50, v62 offset0:32 offset1:48
	ds_write2_b32 v6, v51, v63 offset0:97 offset1:113
	ds_write2_b32 v6, v52, v64 offset0:162 offset1:178
	ds_write2_b32 v6, v53, v65 offset0:227 offset1:243
	ds_write2_b32 v6, v58, v14 offset0:64 offset1:80
	ds_write2_b32 v6, v59, v15 offset0:129 offset1:145
	ds_write2_b32 v6, v60, v16 offset0:194 offset1:210
	v_add_u32_e32 v6, 0x2400, v177
	ds_write2_b32 v6, v61, v17 offset0:3 offset1:19
	v_add_u32_e32 v6, 0x3000, v177
	v_add_u32_e32 v7, 0x3200, v177
	s_or_b32 s36, s22, s71
	ds_write2_b32 v6, v22, v18 offset0:48 offset1:64
	ds_write2_b32 v6, v23, v19 offset0:113 offset1:129
	ds_write2_b32 v6, v24, v20 offset0:178 offset1:194
	ds_write2_b32 v7, v25, v21 offset0:115 offset1:131
	ds_write2_b32 v6, v10, v2 offset0:80 offset1:96
	ds_write2_b32 v6, v11, v3 offset0:145 offset1:161
	ds_write2_b32 v6, v12, v4 offset0:210 offset1:226
	v_add_u32_e32 v2, 0x3400, v177
	s_cmpk_lt_i32 s36, 0xd10
	ds_write2_b32 v2, v13, v5 offset0:19 offset1:35
	s_cbranch_scc0 .LBB0_345
	s_add_i32 s76, s26, s70
	s_cmpk_lt_i32 s36, 0xd00
	s_mov_b64 s[26:27], -1
	s_cbranch_scc0 .LBB0_391
	s_cmpk_gt_i32 s76, 0xfff
	s_cselect_b64 s[48:49], -1, 0
	s_cmpk_gt_i32 s36, 0x3ff
	s_mov_b64 s[52:53], -1
	s_cbranch_scc0 .LBB0_371
	s_cmpk_gt_u32 s22, 0x5ff
	s_cbranch_scc0 .LBB0_368
	s_cmpk_lt_u32 s22, 0x700
	s_mov_b64 s[52:53], 0
	s_cbranch_scc1 .LBB0_359
	s_cmpk_gt_u32 s22, 0x7ff
	s_mov_b64 s[62:63], -1
	s_cbranch_scc0 .LBB0_366
	s_cmpk_gt_u32 s22, 0x8ff
	s_mov_b64 s[56:57], -1
	s_cbranch_scc0 .LBB0_364
	s_cmpk_lt_u32 s22, 0xa00
	s_mov_b64 s[56:57], 0
	s_cbranch_scc1 .LBB0_360
	s_cmpk_gt_u32 s22, 0xaff
	s_mov_b64 s[58:59], -1
	s_cbranch_scc0 .LBB0_362
	s_cmpk_gt_u32 s22, 0xbff
	s_mov_b64 s[58:59], 0
	s_cbranch_scc1 .LBB0_361
	s_add_i32 s77, s36, 0xfffff500
	s_mov_b64 s[34:35], 0x100
	s_mov_b64 s[46:47], 0xb778000
	s_mov_b64 s[60:61], -1
	s_mov_b64 s[26:27], 0
	s_branch .LBB0_362
